# diff-attn: relative-position bias table LDS read hoisted to the loop head so its latency hides under the QK MFMAs
# baseline (speedup 1.0000x reference)
; DI f4 mfma16(h8 a, h8 b, f4 c) { return __builtin_amdgcn_mfma_f32_16x16x32_f16(a, b, c, 0, 0, 0); }
; template <int DQK, bool BIAS>
; __device__ __forceinline__ void attn_pass(const hf* __restrict__ Q, int ldq, const hf* __restrict__ Kp, int ldk, const hf* __restrict__ VT,
;                                           int s0, int L, int q0, float scale_l2, const float* sBias, f4 (&oacc)[8][4], char* smem) {
;     ...
;   for (int kt = 0; kt < nkt; ++kt) {
;     const hf* sK = sbase + (kt & 1) * A_STG; const hf* sVT = sK + 64 * 104;
;     f4 sacc[4][4];
; #pragma unroll
;     for (int mk = 0; mk < 4; ++mk) {
;       h8 kf[NKS];
; #pragma unroll
;       for (int ks = 0; ks < NKS; ++ks) kf[ks] = *(const h8*)(sK + (mk * 16 + fr) * KS + ks * 32 + (fq ^ (((fr >> 2) ^ (fr >> 3)) & 1)) * 8);
; #pragma unroll
;       for (int nq = 0; nq < 4; ++nq) {
;         f4 a = {0.f, 0.f, 0.f, 0.f};
; #pragma unroll
;         for (int ks = 0; ks < NKS; ++ks) a = mfma16(kf[ks], qf[nq][ks], a);
;         sacc[mk][nq] = a;
;       }
;     }
;     if (kt + 1 < nkt) storeKV((kt + 1) & 1);
;     ...
;       const int dmin = key0 - (q0 + 255), dmax = key0 + 63 - q0;
;       uni = (dmax <= -91) || (dmin >= 91);
;       add = dmax <= -91 ? sBias[0] : sBias[256];
.LBB0_1948:
	s_bitcmp1_b32 s16, 0
	s_cselect_b32 s17, 0x7c00, 0
	s_add_i32 s95, s17, 16
	s_add_i32 s94, s16, 1
	s_waitcnt lgkmcnt(0)
	s_add_i32 s26, s93, s20
	s_add_i32 s26, s26, 0xffffff80
	s_cmpk_lt_i32 s26, 0xff67
	s_mov_b32 s26, 0xfc00
	s_cselect_b32 s26, 0xf800, s26
	s_add_i32 s26, s26, 16
	v_mov_b32_e32 v70, s26
	ds_read_b32 v196, v70
	v_mfma_f32_16x16x32_f16 v[188:191], v[72:75], v[0:3], 0
	v_mfma_f32_16x16x32_f16 v[188:191], v[76:79], v[4:7], v[188:191]
	v_mfma_f32_16x16x32_f16 v[156:159], v[72:75], v[16:19], 0
	v_mfma_f32_16x16x32_f16 v[172:175], v[72:75], v[8:11], 0
	v_mfma_f32_16x16x32_f16 v[156:159], v[76:79], v[20:23], v[156:159]
	v_mfma_f32_16x16x32_f16 v[124:127], v[72:75], v[24:27], 0
	v_mfma_f32_16x16x32_f16 v[172:175], v[76:79], v[12:15], v[172:175]
	v_mfma_f32_16x16x32_f16 v[124:127], v[76:79], v[28:31], v[124:127]
	s_cmp_ge_u32 s94, s73
	s_cbranch_scc1 .Lqk_noW
	v_mfma_f32_16x16x32_f16 v[184:187], v[48:51], v[0:3], 0
	s_bitcmp1_b32 s94, 0
	s_cselect_b32 s17, 0x7c00, 0
	v_mfma_f32_16x16x32_f16 v[184:187], v[52:55], v[4:7], v[184:187]
	s_add_i32 s17, s17, 16
	v_add3_u32 v68, s17, v211, v244
	v_mfma_f32_16x16x32_f16 v[168:171], v[48:51], v[8:11], 0
	s_waitcnt vmcnt(1)
	ds_write_b128 v68, a[200:203]
	v_mfma_f32_16x16x32_f16 v[168:171], v[52:55], v[12:15], v[168:171]
	s_waitcnt vmcnt(0)
	ds_write_b128 v68, a[204:207] offset:64
	v_mfma_f32_16x16x32_f16 v[152:155], v[48:51], v[16:19], 0
	v_add3_u32 v68, s17, v232, v210
	v_mfma_f32_16x16x32_f16 v[152:155], v[52:55], v[20:23], v[152:155]
	ds_write_b128 v68, a[192:195] offset:13312
	v_mfma_f32_16x16x32_f16 v[120:123], v[48:51], v[24:27], 0
	v_add3_u32 v68, s17, v234, v210
	v_mfma_f32_16x16x32_f16 v[120:123], v[52:55], v[28:31], v[120:123]
	ds_write_b128 v68, a[196:199] offset:13312
	v_mfma_f32_16x16x32_f16 v[180:183], v[56:59], v[0:3], 0
	v_add3_u32 v68, s17, v235, v210
	v_mfma_f32_16x16x32_f16 v[180:183], v[60:63], v[4:7], v[180:183]
	ds_write_b128 v68, a[208:211] offset:13312
	v_mfma_f32_16x16x32_f16 v[164:167], v[56:59], v[8:11], 0
	v_add3_u32 v68, s17, v236, v210
	v_mfma_f32_16x16x32_f16 v[164:167], v[60:63], v[12:15], v[164:167]
	ds_write_b128 v68, a[212:215] offset:13312
	s_branch .Lqk_joinW

; template <int DQK, bool BIAS>
; __device__ __forceinline__ void attn_pass(const hf* __restrict__ Q, int ldq, const hf* __restrict__ Kp, int ldk, const hf* __restrict__ VT,
;                                           int s0, int L, int q0, float scale_l2, const float* sBias, f4 (&oacc)[8][4], char* smem) {
;     ...
;     if (BIAS) {
;       const int dmin = key0 - (q0 + 255), dmax = key0 + 63 - q0;
;       uni = (dmax <= -91) || (dmin >= 91);
;       add = dmax <= -91 ? sBias[0] : sBias[256];
;     }
; #pragma unroll
;     for (int nq = 0; nq < 4; ++nq) {
;       if (BIAS) {
;         if (uni) {
; #pragma unroll
;           for (int mk = 0; mk < 4; ++mk)
; #pragma unroll
;             for (int j = 0; j < 4; ++j) sacc[mk][nq][j] = sacc[mk][nq][j] * scale_l2 + add;
;         } else {
; #pragma unroll
;           for (int mk = 0; mk < 4; ++mk)
; #pragma unroll
;             for (int j = 0; j < 4; ++j) {
;               int rel = (key0 + mk * 16 + fq * 4 + j) - (q0 + wv * 64 + nq * 16 + fr);
;               rel = min(max(rel, -128), 128);
;               sacc[mk][nq][j] = sacc[mk][nq][j] * scale_l2 + sBias[rel + 128];
;             }
.LBB0_1952:
	s_add_i32 s16, s93, s20
	s_add_i32 s17, s16, 0xffffff80
	s_addk_i32 s16, 0xfe26
	s_cmp_gt_u32 s16, 0xfffffe0c
	s_cselect_b64 s[26:27], -1, 0
	s_cmpk_lt_i32 s17, 0xff67
	s_mov_b32 s17, 0xfc00
	s_cselect_b32 s17, 0xf800, s17
	s_add_i32 s17, s17, 16
	v_add_u32_e32 v252, s20, v241
	s_cmp_lt_u32 s16, 0xfffffe0d
	s_cbranch_scc1 .Lattn_fast
	s_mov_b64 s[16:17], -1
	v_add_u32_e32 v251, 0xffffff80, v252
	v_add_u32_e32 v250, 0xffffff81, v252
	v_add_u32_e32 v249, 0xffffff82, v252
	v_add_u32_e32 v248, 0xffffff83, v252
	v_add_u32_e32 v229, 0xffffff90, v252
	v_add_u32_e32 v228, 0xffffff91, v252
	v_add_u32_e32 v227, 0xffffff92, v252
	v_add_u32_e32 v230, 0xffffff93, v252
	v_add_u32_e32 v222, 0xffffffa0, v252
	v_add_u32_e32 v195, 0xffffffa1, v252
	v_add_u32_e32 v194, 0xffffffa2, v252
	v_add_u32_e32 v225, 0xffffffa3, v252
	v_med3_i32 v32, v251, s2, v223
	v_med3_i32 v33, v250, s2, v223
	v_med3_i32 v34, v249, s2, v223
	v_med3_i32 v35, v248, s2, v223
	v_med3_i32 v36, v229, s2, v223
	v_med3_i32 v37, v228, s2, v223
	v_med3_i32 v38, v227, s2, v223
	v_med3_i32 v39, v230, s2, v223
	v_med3_i32 v40, v222, s2, v223
	v_med3_i32 v41, v195, s2, v223
	v_med3_i32 v42, v194, s2, v223
	v_med3_i32 v43, v225, s2, v223
	v_add_u32_e32 v44, 0xffffffb0, v252
	v_add_u32_e32 v45, 0xffffffb1, v252
	v_add_u32_e32 v46, 0xffffffb2, v252
	v_add_u32_e32 v47, 0xffffffb3, v252
	v_lshl_add_u32 v32, v32, 2, 16
	v_lshl_add_u32 v33, v33, 2, 16
	v_lshl_add_u32 v34, v34, 2, 16
	v_lshl_add_u32 v35, v35, 2, 16
	v_lshl_add_u32 v36, v36, 2, 16
	v_lshl_add_u32 v37, v37, 2, 16
	v_lshl_add_u32 v38, v38, 2, 16
	v_lshl_add_u32 v39, v39, 2, 16
	v_lshl_add_u32 v40, v40, 2, 16
	v_lshl_add_u32 v41, v41, 2, 16
	v_lshl_add_u32 v42, v42, 2, 16
	v_lshl_add_u32 v43, v43, 2, 16
	v_med3_i32 v44, v44, s2, v223
	v_med3_i32 v45, v45, s2, v223
	v_med3_i32 v46, v46, s2, v223
	v_med3_i32 v47, v47, s2, v223
	ds_read_b32 v32, v32 offset:64000
	ds_read_b32 v33, v33 offset:64000
	ds_read_b32 v34, v34 offset:64000
	ds_read_b32 v35, v35 offset:64000
	ds_read_b32 v36, v36 offset:64000
	ds_read_b32 v37, v37 offset:64000
	ds_read_b32 v38, v38 offset:64000
	ds_read_b32 v39, v39 offset:64000
	v_lshl_add_u32 v44, v44, 2, 16
	v_lshl_add_u32 v45, v45, 2, 16
	v_lshl_add_u32 v46, v46, 2, 16
	v_lshl_add_u32 v47, v47, 2, 16
	ds_read_b32 v40, v40 offset:64000
	ds_read_b32 v41, v41 offset:64000
	ds_read_b32 v42, v42 offset:64000
	ds_read_b32 v43, v43 offset:64000
	ds_read_b32 v202, v44 offset:64000
	ds_read_b32 v203, v45 offset:64000
	ds_read_b32 v204, v46 offset:64000
	ds_read_b32 v205, v47 offset:64000
	s_waitcnt lgkmcnt(12)
	v_pk_fma_f32 v[34:35], v[190:191], s[22:23], v[34:35] op_sel_hi:[1,0,1]
	v_pk_fma_f32 v[32:33], v[188:189], s[22:23], v[32:33] op_sel_hi:[1,0,1]
	s_waitcnt lgkmcnt(8)
	v_pk_fma_f32 v[46:47], v[186:187], s[22:23], v[38:39] op_sel_hi:[1,0,1]
	v_pk_fma_f32 v[44:45], v[184:185], s[22:23], v[36:37] op_sel_hi:[1,0,1]
	s_waitcnt lgkmcnt(4)
	v_pk_fma_f32 v[42:43], v[182:183], s[22:23], v[42:43] op_sel_hi:[1,0,1]
	v_pk_fma_f32 v[40:41], v[180:181], s[22:23], v[40:41] op_sel_hi:[1,0,1]
	s_waitcnt lgkmcnt(0)
	v_pk_fma_f32 v[38:39], v[178:179], s[22:23], v[204:205] op_sel_hi:[1,0,1]
	v_pk_fma_f32 v[36:37], v[176:177], s[22:23], v[202:203] op_sel_hi:[1,0,1]
	s_mov_b64 s[16:17], 0
